# compression MLP first matmul: 72 operand loads streamed through a 23-quad register ring with exact counted waits (was 18 loads + full wait per K step)
# speedup vs baseline: 1.0030x; 1.0013x over previous
.LBB0_550:
	v_ashrrev_i32_e32 v59, 1, v58
	v_add_u32_e32 v59, v59, v53
	v_lshl_add_u64 v[60:61], v[54:55], 0, s[8:9]
	s_mov_b32 s13, 0x4b80000
	v_min_i32_e32 v59, 0x1fff, v59
	v_add_co_u32_e32 v90, vcc, s13, v60
	v_add_u32_e32 v59, s3, v59
	s_nop 0
	v_addc_co_u32_e32 v91, vcc, 0, v61, vcc
	v_mad_i64_i32 v[106:107], s[30:31], v59, s23, v[56:57]
	s_mov_b32 s13, 0x4b90000
	v_add_co_u32_e64 v94, s[44:45], s13, v60
	s_mov_b32 s13, 0x4ba0000
	s_nop 0
	v_addc_co_u32_e64 v95, vcc, 0, v61, s[44:45]
	v_add_co_u32_e64 v96, s[46:47], s13, v60
	s_mov_b32 s13, 0x4bb0000
	s_nop 0
	v_addc_co_u32_e64 v97, vcc, 0, v61, s[46:47]
	v_add_co_u32_e64 v98, s[48:49], s13, v60
	s_mov_b32 s13, 0x4bc0000
	s_nop 0
	v_addc_co_u32_e64 v99, vcc, 0, v61, s[48:49]
	v_add_co_u32_e64 v100, s[50:51], s13, v60
	s_mov_b32 s13, 0x4bd0000
	s_nop 0
	v_addc_co_u32_e64 v101, vcc, 0, v61, s[50:51]
	v_add_co_u32_e64 v102, s[52:53], s13, v60
	s_mov_b32 s13, 0x4be0000
	s_nop 0
	v_addc_co_u32_e64 v103, vcc, 0, v61, s[52:53]
	v_add_co_u32_e64 v104, s[54:55], s13, v60
	s_mov_b32 s13, 0x4bf0000
	s_nop 0
	v_addc_co_u32_e64 v105, vcc, 0, v61, s[54:55]
	v_add_co_u32_e64 v60, s[56:57], s13, v60
	s_nop 0
	v_addc_co_u32_e64 v61, vcc, 0, v61, s[56:57]
	v_add_u32_e32 v59, 2, v72
	v_ashrrev_i32_e32 v59, 1, v59
	v_add_u32_e32 v59, v59, v53
	v_min_i32_e32 v59, 0x1fff, v59
	v_add_u32_e32 v59, s3, v59
	v_mad_i64_i32 v[172:173], s[30:31], v59, s23, v[56:57]
	v_add_u32_e32 v59, 4, v72
	v_ashrrev_i32_e32 v59, 1, v59
	v_add_u32_e32 v59, v59, v53
	v_min_i32_e32 v59, 0x1fff, v59
	v_add_u32_e32 v59, s3, v59
	v_mad_i64_i32 v[154:155], s[30:31], v59, s23, v[56:57]
	v_add_u32_e32 v59, 6, v72
	v_ashrrev_i32_e32 v59, 1, v59
	v_add_u32_e32 v59, v59, v53
	v_min_i32_e32 v59, 0x1fff, v59
	v_add_u32_e32 v59, s3, v59
	v_mad_i64_i32 v[116:117], s[30:31], v59, s23, v[56:57]
	global_load_dwordx4 v[212:215], v[106:107], off
	global_load_dwordx4 v[216:219], v[90:91], off
	global_load_dwordx4 v[220:223], v[94:95], off
	global_load_dwordx4 v[224:227], v[96:97], off
	global_load_dwordx4 v[228:231], v[98:99], off
	global_load_dwordx4 v[232:235], v[100:101], off
	global_load_dwordx4 v[236:239], v[102:103], off
	global_load_dwordx4 v[240:243], v[104:105], off
	global_load_dwordx4 v[244:247], v[60:61], off
	global_load_dwordx4 v[248:251], v[106:107], off offset:64
	global_load_dwordx4 v[138:141], v[90:91], off offset:64
	global_load_dwordx4 v[142:145], v[94:95], off offset:64
	global_load_dwordx4 v[146:149], v[96:97], off offset:64
	global_load_dwordx4 v[150:153], v[98:99], off offset:64
	global_load_dwordx4 v[176:179], v[100:101], off offset:64
	global_load_dwordx4 v[180:183], v[102:103], off offset:64
	global_load_dwordx4 v[184:187], v[104:105], off offset:64
	global_load_dwordx4 v[164:167], v[60:61], off offset:64
	global_load_dwordx4 v[168:171], v[172:173], off
	global_load_dwordx4 v[108:111], v[90:91], off offset:128
	global_load_dwordx4 v[112:115], v[94:95], off offset:128
	global_load_dwordx4 v[82:85], v[96:97], off offset:128
	global_load_dwordx4 v[86:89], v[98:99], off offset:128
	s_waitcnt vmcnt(21)
	v_mfma_f32_16x16x32_bf16 v[2:5], v[212:215], v[216:219], v[2:5]
	global_load_dwordx4 v[216:219], v[100:101], off offset:128
	s_waitcnt vmcnt(21)
	v_mfma_f32_16x16x32_bf16 v[6:9], v[212:215], v[220:223], v[6:9]
	global_load_dwordx4 v[220:223], v[102:103], off offset:128
	s_waitcnt vmcnt(21)
	v_mfma_f32_16x16x32_bf16 v[10:13], v[212:215], v[224:227], v[10:13]
	global_load_dwordx4 v[224:227], v[104:105], off offset:128
	s_waitcnt vmcnt(21)
	v_mfma_f32_16x16x32_bf16 v[14:17], v[212:215], v[228:231], v[14:17]
	global_load_dwordx4 v[228:231], v[60:61], off offset:128
	s_waitcnt vmcnt(21)
	v_mfma_f32_16x16x32_bf16 v[18:21], v[212:215], v[232:235], v[18:21]
	global_load_dwordx4 v[232:235], v[172:173], off offset:64
	s_waitcnt vmcnt(21)
	v_mfma_f32_16x16x32_bf16 v[22:25], v[212:215], v[236:239], v[22:25]
	global_load_dwordx4 v[236:239], v[90:91], off offset:192
	s_waitcnt vmcnt(21)
	v_mfma_f32_16x16x32_bf16 v[26:29], v[212:215], v[240:243], v[26:29]
	global_load_dwordx4 v[240:243], v[94:95], off offset:192
	s_waitcnt vmcnt(21)
	v_mfma_f32_16x16x32_bf16 v[30:33], v[212:215], v[244:247], v[30:33]
	global_load_dwordx4 v[244:247], v[96:97], off offset:192
	global_load_dwordx4 v[212:215], v[98:99], off offset:192
	s_waitcnt vmcnt(21)
	v_mfma_f32_16x16x32_bf16 v[2:5], v[248:251], v[138:141], v[2:5]
	global_load_dwordx4 v[138:141], v[100:101], off offset:192
	s_waitcnt vmcnt(21)
	v_mfma_f32_16x16x32_bf16 v[6:9], v[248:251], v[142:145], v[6:9]
	global_load_dwordx4 v[142:145], v[102:103], off offset:192
	s_waitcnt vmcnt(21)
	v_mfma_f32_16x16x32_bf16 v[10:13], v[248:251], v[146:149], v[10:13]
	global_load_dwordx4 v[146:149], v[104:105], off offset:192
	s_waitcnt vmcnt(21)
	v_mfma_f32_16x16x32_bf16 v[14:17], v[248:251], v[150:153], v[14:17]
	global_load_dwordx4 v[150:153], v[60:61], off offset:192
	s_waitcnt vmcnt(21)
	v_mfma_f32_16x16x32_bf16 v[18:21], v[248:251], v[176:179], v[18:21]
	global_load_dwordx4 v[176:179], v[154:155], off
	s_waitcnt vmcnt(21)
	v_mfma_f32_16x16x32_bf16 v[22:25], v[248:251], v[180:183], v[22:25]
	global_load_dwordx4 v[180:183], v[90:91], off offset:256
	s_waitcnt vmcnt(21)
	v_mfma_f32_16x16x32_bf16 v[26:29], v[248:251], v[184:187], v[26:29]
	global_load_dwordx4 v[184:187], v[94:95], off offset:256
	s_waitcnt vmcnt(21)
	v_mfma_f32_16x16x32_bf16 v[30:33], v[248:251], v[164:167], v[30:33]
	global_load_dwordx4 v[164:167], v[96:97], off offset:256
	global_load_dwordx4 v[248:251], v[98:99], off offset:256
	s_waitcnt vmcnt(21)
	v_mfma_f32_16x16x32_bf16 v[2:5], v[168:171], v[108:111], v[2:5]
	global_load_dwordx4 v[108:111], v[100:101], off offset:256
	s_waitcnt vmcnt(21)
	v_mfma_f32_16x16x32_bf16 v[6:9], v[168:171], v[112:115], v[6:9]
	global_load_dwordx4 v[112:115], v[102:103], off offset:256
	s_waitcnt vmcnt(21)
	v_mfma_f32_16x16x32_bf16 v[10:13], v[168:171], v[82:85], v[10:13]
	global_load_dwordx4 v[82:85], v[104:105], off offset:256
	s_waitcnt vmcnt(21)
	v_mfma_f32_16x16x32_bf16 v[14:17], v[168:171], v[86:89], v[14:17]
	global_load_dwordx4 v[86:89], v[60:61], off offset:256
	s_waitcnt vmcnt(21)
	v_mfma_f32_16x16x32_bf16 v[18:21], v[168:171], v[216:219], v[18:21]
	global_load_dwordx4 v[216:219], v[154:155], off offset:64
	s_waitcnt vmcnt(21)
	v_mfma_f32_16x16x32_bf16 v[22:25], v[168:171], v[220:223], v[22:25]
	global_load_dwordx4 v[220:223], v[90:91], off offset:320
	s_waitcnt vmcnt(21)
	v_mfma_f32_16x16x32_bf16 v[26:29], v[168:171], v[224:227], v[26:29]
	global_load_dwordx4 v[224:227], v[94:95], off offset:320
	s_waitcnt vmcnt(21)
	v_mfma_f32_16x16x32_bf16 v[30:33], v[168:171], v[228:231], v[30:33]
	global_load_dwordx4 v[228:231], v[96:97], off offset:320
	global_load_dwordx4 v[168:171], v[98:99], off offset:320
	s_waitcnt vmcnt(21)
	v_mfma_f32_16x16x32_bf16 v[2:5], v[232:235], v[236:239], v[2:5]
	global_load_dwordx4 v[236:239], v[100:101], off offset:320
	s_waitcnt vmcnt(21)
	v_mfma_f32_16x16x32_bf16 v[6:9], v[232:235], v[240:243], v[6:9]
	global_load_dwordx4 v[240:243], v[102:103], off offset:320
	s_waitcnt vmcnt(21)
	v_mfma_f32_16x16x32_bf16 v[10:13], v[232:235], v[244:247], v[10:13]
	global_load_dwordx4 v[244:247], v[104:105], off offset:320
	s_waitcnt vmcnt(21)
	v_mfma_f32_16x16x32_bf16 v[14:17], v[232:235], v[212:215], v[14:17]
	global_load_dwordx4 v[212:215], v[60:61], off offset:320
	s_waitcnt vmcnt(21)
	v_mfma_f32_16x16x32_bf16 v[18:21], v[232:235], v[138:141], v[18:21]
	global_load_dwordx4 v[138:141], v[116:117], off
	s_waitcnt vmcnt(21)
	v_mfma_f32_16x16x32_bf16 v[22:25], v[232:235], v[142:145], v[22:25]
	global_load_dwordx4 v[142:145], v[90:91], off offset:384
	s_waitcnt vmcnt(21)
	v_mfma_f32_16x16x32_bf16 v[26:29], v[232:235], v[146:149], v[26:29]
	global_load_dwordx4 v[146:149], v[94:95], off offset:384
	s_waitcnt vmcnt(21)
	v_mfma_f32_16x16x32_bf16 v[30:33], v[232:235], v[150:153], v[30:33]
	global_load_dwordx4 v[150:153], v[96:97], off offset:384
	global_load_dwordx4 v[232:235], v[98:99], off offset:384
	s_waitcnt vmcnt(21)
	v_mfma_f32_16x16x32_bf16 v[2:5], v[176:179], v[180:183], v[2:5]
	global_load_dwordx4 v[180:183], v[100:101], off offset:384
	s_waitcnt vmcnt(21)
	v_mfma_f32_16x16x32_bf16 v[6:9], v[176:179], v[184:187], v[6:9]
	global_load_dwordx4 v[184:187], v[102:103], off offset:384
	s_waitcnt vmcnt(21)
	v_mfma_f32_16x16x32_bf16 v[10:13], v[176:179], v[164:167], v[10:13]
	global_load_dwordx4 v[164:167], v[104:105], off offset:384
	s_waitcnt vmcnt(21)
	v_mfma_f32_16x16x32_bf16 v[14:17], v[176:179], v[248:251], v[14:17]
	global_load_dwordx4 v[248:251], v[60:61], off offset:384
	s_waitcnt vmcnt(21)
	v_mfma_f32_16x16x32_bf16 v[18:21], v[176:179], v[108:111], v[18:21]
	global_load_dwordx4 v[108:111], v[116:117], off offset:64
	s_waitcnt vmcnt(21)
	v_mfma_f32_16x16x32_bf16 v[22:25], v[176:179], v[112:115], v[22:25]
	global_load_dwordx4 v[112:115], v[90:91], off offset:448
	s_waitcnt vmcnt(21)
	v_mfma_f32_16x16x32_bf16 v[26:29], v[176:179], v[82:85], v[26:29]
	global_load_dwordx4 v[82:85], v[94:95], off offset:448
	s_waitcnt vmcnt(21)
	v_mfma_f32_16x16x32_bf16 v[30:33], v[176:179], v[86:89], v[30:33]
	global_load_dwordx4 v[86:89], v[96:97], off offset:448
	global_load_dwordx4 v[176:179], v[98:99], off offset:448
	s_waitcnt vmcnt(21)
	v_mfma_f32_16x16x32_bf16 v[2:5], v[216:219], v[220:223], v[2:5]
	global_load_dwordx4 v[220:223], v[100:101], off offset:448
	s_waitcnt vmcnt(21)
	v_mfma_f32_16x16x32_bf16 v[6:9], v[216:219], v[224:227], v[6:9]
	global_load_dwordx4 v[224:227], v[102:103], off offset:448
	s_waitcnt vmcnt(21)
	v_mfma_f32_16x16x32_bf16 v[10:13], v[216:219], v[228:231], v[10:13]
	global_load_dwordx4 v[228:231], v[104:105], off offset:448
	s_waitcnt vmcnt(21)
	v_mfma_f32_16x16x32_bf16 v[14:17], v[216:219], v[168:171], v[14:17]
	global_load_dwordx4 v[168:171], v[60:61], off offset:448
	s_waitcnt vmcnt(21)
	v_mfma_f32_16x16x32_bf16 v[18:21], v[216:219], v[236:239], v[18:21]
	s_waitcnt vmcnt(20)
	v_mfma_f32_16x16x32_bf16 v[22:25], v[216:219], v[240:243], v[22:25]
	s_waitcnt vmcnt(19)
	v_mfma_f32_16x16x32_bf16 v[26:29], v[216:219], v[244:247], v[26:29]
	s_waitcnt vmcnt(18)
	v_mfma_f32_16x16x32_bf16 v[30:33], v[216:219], v[212:215], v[30:33]
	s_waitcnt vmcnt(16)
	v_mfma_f32_16x16x32_bf16 v[2:5], v[138:141], v[142:145], v[2:5]
	s_waitcnt vmcnt(15)
	v_mfma_f32_16x16x32_bf16 v[6:9], v[138:141], v[146:149], v[6:9]
	s_waitcnt vmcnt(14)
	v_mfma_f32_16x16x32_bf16 v[10:13], v[138:141], v[150:153], v[10:13]
	s_waitcnt vmcnt(13)
	v_mfma_f32_16x16x32_bf16 v[14:17], v[138:141], v[232:235], v[14:17]
	s_waitcnt vmcnt(12)
	v_mfma_f32_16x16x32_bf16 v[18:21], v[138:141], v[180:183], v[18:21]
	s_waitcnt vmcnt(11)
	v_mfma_f32_16x16x32_bf16 v[22:25], v[138:141], v[184:187], v[22:25]
	s_waitcnt vmcnt(10)
	v_mfma_f32_16x16x32_bf16 v[26:29], v[138:141], v[164:167], v[26:29]
	s_waitcnt vmcnt(9)
	v_mfma_f32_16x16x32_bf16 v[30:33], v[138:141], v[248:251], v[30:33]
	s_waitcnt vmcnt(7)
	v_mfma_f32_16x16x32_bf16 v[2:5], v[108:111], v[112:115], v[2:5]
	s_waitcnt vmcnt(6)
	v_mfma_f32_16x16x32_bf16 v[6:9], v[108:111], v[82:85], v[6:9]
	s_waitcnt vmcnt(5)
	v_mfma_f32_16x16x32_bf16 v[10:13], v[108:111], v[86:89], v[10:13]
	s_waitcnt vmcnt(4)
	v_mfma_f32_16x16x32_bf16 v[14:17], v[108:111], v[176:179], v[14:17]
	s_waitcnt vmcnt(3)
	v_mfma_f32_16x16x32_bf16 v[18:21], v[108:111], v[220:223], v[18:21]
	s_waitcnt vmcnt(2)
	v_mfma_f32_16x16x32_bf16 v[22:25], v[108:111], v[224:227], v[22:25]
	s_waitcnt vmcnt(1)
	v_mfma_f32_16x16x32_bf16 v[26:29], v[108:111], v[228:231], v[26:29]
	s_waitcnt vmcnt(0)
	v_mfma_f32_16x16x32_bf16 v[30:33], v[108:111], v[168:171], v[30:33]
	v_add_u32_e32 v53, 0x4000, v79
	ds_write2_b32 v53, v2, v6 offset1:16
	ds_write2_b32 v53, v3, v7 offset0:132 offset1:148
	v_add_u32_e32 v2, 0x4400, v79
	ds_write2_b32 v2, v4, v8 offset0:8 offset1:24
	ds_write2_b32 v2, v5, v9 offset0:140 offset1:156
	ds_write2_b32 v53, v10, v14 offset0:32 offset1:48
	ds_write2_b32 v53, v11, v15 offset0:164 offset1:180
	ds_write2_b32 v2, v12, v16 offset0:40 offset1:56
	ds_write2_b32 v2, v13, v17 offset0:172 offset1:188
	ds_write2_b32 v53, v18, v22 offset0:64 offset1:80
	ds_write2_b32 v53, v19, v23 offset0:196 offset1:212
	ds_write2_b32 v2, v20, v24 offset0:72 offset1:88
	ds_write2_b32 v2, v21, v25 offset0:204 offset1:220
	ds_write2_b32 v53, v26, v30 offset0:96 offset1:112
	ds_write2_b32 v53, v27, v31 offset0:228 offset1:244
	ds_write2_b32 v2, v28, v32 offset0:104 offset1:120
	ds_write2_b32 v2, v29, v33 offset0:236 offset1:252
	s_waitcnt lgkmcnt(0)
	s_barrier
	ds_read_b128 v[2:5], v74 offset:16384
	s_movk_i32 s8, 0x7fff
	s_waitcnt lgkmcnt(0)
	v_pk_add_f32 v[6:7], v[4:5], 0 op_sel_hi:[1,0]
	v_pk_add_f32 v[8:9], v[2:3], 0 op_sel_hi:[1,0]
	ds_read_b128 v[2:5], v74 offset:24832
	s_waitcnt lgkmcnt(0)
	v_pk_add_f32 v[6:7], v[6:7], v[4:5]
	v_pk_add_f32 v[8:9], v[8:9], v[2:3]
	ds_read_b128 v[2:5], v74 offset:33280
	s_waitcnt lgkmcnt(0)
	v_pk_add_f32 v[6:7], v[6:7], v[4:5]
	v_pk_add_f32 v[8:9], v[8:9], v[2:3]
	ds_read_b128 v[2:5], v74 offset:41728
	s_waitcnt lgkmcnt(0)
	v_pk_add_f32 v[6:7], v[6:7], v[4:5]
	v_pk_add_f32 v[8:9], v[8:9], v[2:3]
	ds_read_b128 v[2:5], v74 offset:50176
	s_waitcnt lgkmcnt(0)
	v_pk_add_f32 v[6:7], v[6:7], v[4:5]
	v_pk_add_f32 v[8:9], v[8:9], v[2:3]
	ds_read_b128 v[2:5], v74 offset:58624
	s_waitcnt lgkmcnt(0)
	v_pk_add_f32 v[6:7], v[6:7], v[4:5]
	v_pk_add_f32 v[8:9], v[8:9], v[2:3]
	ds_read_b128 v[2:5], v75 offset:50688
	s_waitcnt lgkmcnt(0)
	v_pk_add_f32 v[6:7], v[6:7], v[4:5]
	v_pk_add_f32 v[8:9], v[8:9], v[2:3]
	ds_read_b128 v[2:5], v75 offset:59136
	s_waitcnt lgkmcnt(0)
	v_pk_add_f32 v[8:9], v[8:9], v[2:3]
	v_or_b32_e32 v2, s2, v73
	v_ashrrev_i32_e32 v3, 31, v2
	v_lshl_add_u64 v[2:3], v[2:3], 2, s[14:15]
	v_pk_add_f32 v[6:7], v[6:7], v[4:5]
	global_load_dwordx4 v[2:5], v[2:3], off
	s_waitcnt vmcnt(0)
	v_mov_b32_e32 v10, v3
	v_mov_b32_e32 v11, v4
	v_mov_b32_e32 v3, v5
	v_mov_b32_e32 v5, v7
	v_pk_mov_b32 v[6:7], v[8:9], v[6:7] op_sel:[1,0]
	v_mov_b32_e32 v4, v8
	v_pk_add_f32 v[6:7], v[6:7], v[10:11]
	v_pk_add_f32 v[2:3], v[2:3], v[4:5]
	v_mul_f32_e32 v5, 0x3d372713, v6
	v_mul_f32_e32 v5, v6, v5
	v_fma_f32 v5, v6, v5, v6
	v_mul_f32_e32 v5, 0x3f4c422a, v5
	v_add_f32_e32 v5, v5, v5
	v_mul_f32_e32 v5, 0x3fb8aa3b, v5
	v_exp_f32_e32 v8, v5
	v_mul_f32_e32 v5, 0x3d372713, v7
	v_mul_f32_e32 v5, v7, v5
	v_fma_f32 v5, v7, v5, v7
	v_mul_f32_e32 v5, 0x3f4c422a, v5
	v_add_f32_e32 v5, v5, v5
	v_mul_f32_e32 v5, 0x3fb8aa3b, v5
	v_exp_f32_e32 v9, v5
	v_pk_mul_f32 v[6:7], v[6:7], 0.5 op_sel_hi:[1,0]
	v_mul_f32_e32 v4, 0x3d372713, v2
	v_mul_f32_e32 v4, v2, v4
	v_pk_add_f32 v[8:9], v[8:9], 1.0 op_sel_hi:[1,0]
	v_fma_f32 v4, v2, v4, v2
	v_div_scale_f32 v5, s[2:3], v9, v9, 2.0
	v_rcp_f32_e32 v10, v5
	v_mul_f32_e32 v4, 0x3f4c422a, v4
	v_add_f32_e32 v4, v4, v4
	v_mul_f32_e32 v4, 0x3fb8aa3b, v4
	v_fma_f32 v11, -v5, v10, 1.0
	v_fmac_f32_e32 v10, v11, v10
	v_div_scale_f32 v11, vcc, 2.0, v9, 2.0
	v_mul_f32_e32 v12, v11, v10
	v_fma_f32 v13, -v5, v12, v11
	v_fmac_f32_e32 v12, v13, v10
	v_fma_f32 v5, -v5, v12, v11
	v_div_fmas_f32 v5, v5, v10, v12
	v_div_fixup_f32 v9, v5, v9, 2.0
	v_div_scale_f32 v5, s[2:3], v8, v8, 2.0
	v_rcp_f32_e32 v10, v5
	v_exp_f32_e32 v4, v4
	v_fma_f32 v11, -v5, v10, 1.0
	v_fmac_f32_e32 v10, v11, v10
	v_div_scale_f32 v11, vcc, 2.0, v8, 2.0
	v_mul_f32_e32 v12, v11, v10
	v_fma_f32 v13, -v5, v12, v11
	v_fmac_f32_e32 v12, v13, v10
	v_fma_f32 v5, -v5, v12, v11
	v_div_fmas_f32 v5, v5, v10, v12
	v_div_fixup_f32 v8, v5, v8, 2.0
	v_pk_add_f32 v[8:9], v[8:9], 1.0 op_sel_hi:[1,0] neg_lo:[1,0] neg_hi:[1,0]
	s_nop 0
	v_pk_add_f32 v[8:9], v[8:9], 1.0 op_sel_hi:[1,0]
	s_nop 0
	v_pk_mul_f32 v[6:7], v[6:7], v[8:9]
	s_nop 0
	v_and_b32_sdwa v5, v7, v194 dst_sel:DWORD dst_unused:UNUSED_PAD src0_sel:WORD_1 src1_sel:DWORD
	v_and_b32_sdwa v8, v6, v194 dst_sel:DWORD dst_unused:UNUSED_PAD src0_sel:WORD_1 src1_sel:DWORD
	v_add3_u32 v7, v7, v5, s8
	v_add3_u32 v5, v6, v8, s8
	v_and_b32_e32 v6, 0xffff0000, v5
	v_mul_f32_e32 v5, 0x3d372713, v3
	v_mul_f32_e32 v5, v3, v5
	v_fma_f32 v5, v3, v5, v3
	v_mul_f32_e32 v5, 0x3f4c422a, v5
	v_add_f32_e32 v5, v5, v5
	v_mul_f32_e32 v5, 0x3fb8aa3b, v5
	v_exp_f32_e32 v5, v5
	v_pk_mul_f32 v[2:3], v[2:3], 0.5 op_sel_hi:[1,0]
	v_pk_add_f32 v[4:5], v[4:5], 1.0 op_sel_hi:[1,0]
	s_nop 0
	v_div_scale_f32 v8, s[2:3], v5, v5, 2.0
	v_rcp_f32_e32 v9, v8
	s_nop 0
	v_fma_f32 v10, -v8, v9, 1.0
	v_fmac_f32_e32 v9, v10, v9
	v_div_scale_f32 v10, vcc, 2.0, v5, 2.0
	v_mul_f32_e32 v11, v10, v9
	v_fma_f32 v12, -v8, v11, v10
	v_fmac_f32_e32 v11, v12, v9
	v_fma_f32 v8, -v8, v11, v10
	v_div_fmas_f32 v8, v8, v9, v11
	v_div_fixup_f32 v5, v8, v5, 2.0
	v_div_scale_f32 v8, s[2:3], v4, v4, 2.0
	v_rcp_f32_e32 v9, v8
	s_nop 0
	v_fma_f32 v10, -v8, v9, 1.0
	v_fmac_f32_e32 v9, v10, v9
	v_div_scale_f32 v10, vcc, 2.0, v4, 2.0
	v_mul_f32_e32 v11, v10, v9
	v_fma_f32 v12, -v8, v11, v10
	v_fmac_f32_e32 v11, v12, v9
	v_fma_f32 v8, -v8, v11, v10
	v_div_fmas_f32 v8, v8, v9, v11
	v_div_fixup_f32 v4, v8, v4, 2.0
	v_pk_add_f32 v[4:5], v[4:5], 1.0 op_sel_hi:[1,0] neg_lo:[1,0] neg_hi:[1,0]
	s_nop 0
	v_pk_add_f32 v[4:5], v[4:5], 1.0 op_sel_hi:[1,0]
	s_nop 0
	v_pk_mul_f32 v[2:3], v[2:3], v[4:5]
	s_nop 0
	v_and_b32_sdwa v4, v3, v194 dst_sel:DWORD dst_unused:UNUSED_PAD src0_sel:WORD_1 src1_sel:DWORD
	v_and_b32_sdwa v5, v2, v194 dst_sel:DWORD dst_unused:UNUSED_PAD src0_sel:WORD_1 src1_sel:DWORD
	v_add3_u32 v3, v3, v4, s8
	v_add3_u32 v2, v2, v5, s8
	v_and_b32_e32 v3, 0xffff0000, v3
	v_or_b32_sdwa v3, v3, v7 dst_sel:DWORD dst_unused:UNUSED_PAD src0_sel:DWORD src1_sel:WORD_1
	v_or_b32_sdwa v2, v2, v6 dst_sel:DWORD dst_unused:UNUSED_PAD src0_sel:WORD_1 src1_sel:DWORD
	ds_write_b64 v76, v[2:3]
	s_waitcnt lgkmcnt(0)
	s_barrier
	s_and_saveexec_b64 s[2:3], s[34:35]
	s_cbranch_execz .LBB0_553
	s_ashr_i32 s8, s16, 7
	s_ashr_i32 s9, s8, 31
	s_lshl_b64 s[8:9], s[8:9], 15
	v_lshl_add_u64 v[14:15], v[48:49], 0, s[8:9]
	ds_read_b128 v[2:5], v77
	global_load_dword v6, v[14:15], off
	global_load_dword v7, v[14:15], off offset:256
	global_load_dword v8, v[14:15], off offset:512
	global_load_dword v9, v[14:15], off offset:768
	global_load_dword v10, v[14:15], off offset:1024
	global_load_dword v11, v[14:15], off offset:1280
	global_load_dword v12, v[14:15], off offset:1536
	global_load_dword v13, v[14:15], off offset:1792
	s_movk_i32 s8, 0x2000
	s_waitcnt vmcnt(6)
	v_cvt_pk_bf16_f32 v6, v6, v7
	s_waitcnt vmcnt(4)
	v_cvt_pk_bf16_f32 v7, v8, v9
	s_waitcnt vmcnt(2)
	v_cvt_pk_bf16_f32 v8, v10, v11
	v_add_co_u32_e32 v10, vcc, s8, v14
	s_waitcnt vmcnt(0)
	v_cvt_pk_bf16_f32 v9, v12, v13
	v_addc_co_u32_e32 v11, vcc, 0, v15, vcc
	s_waitcnt lgkmcnt(0)
	v_mfma_f32_16x16x32_bf16 v[2:5], v[2:5], v[6:9], 0
	ds_read_b128 v[6:9], v77 offset:64
	global_load_dword v12, v[10:11], off
	global_load_dword v13, v[10:11], off offset:256
	global_load_dword v16, v[10:11], off offset:512
	global_load_dword v17, v[10:11], off offset:768
	global_load_dword v18, v[10:11], off offset:1024
	global_load_dword v19, v[10:11], off offset:1280
	global_load_dword v20, v[10:11], off offset:1536
	global_load_dword v21, v[10:11], off offset:1792
	s_movk_i32 s8, 0x4000
	s_waitcnt vmcnt(6)
	v_cvt_pk_bf16_f32 v10, v12, v13
	s_waitcnt vmcnt(4)
	v_cvt_pk_bf16_f32 v11, v16, v17
	s_waitcnt vmcnt(2)
	v_cvt_pk_bf16_f32 v12, v18, v19
	s_waitcnt vmcnt(0)
	v_cvt_pk_bf16_f32 v13, v20, v21
	s_waitcnt lgkmcnt(0)
	s_nop 0
	v_mfma_f32_16x16x32_bf16 v[2:5], v[6:9], v[10:13], v[2:5]
	v_add_co_u32_e32 v10, vcc, s8, v14
	ds_read_b128 v[6:9], v77 offset:128
	s_nop 0
	v_addc_co_u32_e32 v11, vcc, 0, v15, vcc
	global_load_dword v12, v[10:11], off
	global_load_dword v13, v[10:11], off offset:256
	global_load_dword v16, v[10:11], off offset:512
	global_load_dword v17, v[10:11], off offset:768
	global_load_dword v18, v[10:11], off offset:1024
	global_load_dword v19, v[10:11], off offset:1280
	global_load_dword v20, v[10:11], off offset:1536
	global_load_dword v21, v[10:11], off offset:1792
	s_movk_i32 s8, 0x6000
	s_waitcnt vmcnt(6)
	v_cvt_pk_bf16_f32 v10, v12, v13
	s_waitcnt vmcnt(4)
	v_cvt_pk_bf16_f32 v11, v16, v17
	s_waitcnt vmcnt(2)
	v_cvt_pk_bf16_f32 v12, v18, v19
	s_waitcnt vmcnt(0)
	v_cvt_pk_bf16_f32 v13, v20, v21
	s_waitcnt lgkmcnt(0)
	s_nop 0
	v_mfma_f32_16x16x32_bf16 v[2:5], v[6:9], v[10:13], v[2:5]
	v_add_co_u32_e32 v10, vcc, s8, v14
	ds_read_b128 v[6:9], v77 offset:192
	s_nop 0
	v_addc_co_u32_e32 v11, vcc, 0, v15, vcc
	global_load_dword v12, v[10:11], off
	global_load_dword v13, v[10:11], off offset:256
	global_load_dword v14, v[10:11], off offset:512
	global_load_dword v15, v[10:11], off offset:768
	global_load_dword v16, v[10:11], off offset:1024
	global_load_dword v17, v[10:11], off offset:1280
	global_load_dword v18, v[10:11], off offset:1536
	global_load_dword v19, v[10:11], off offset:1792
	s_waitcnt vmcnt(6)
	v_cvt_pk_bf16_f32 v10, v12, v13
	s_waitcnt vmcnt(4)
	v_cvt_pk_bf16_f32 v11, v14, v15
	s_waitcnt vmcnt(2)
	v_cvt_pk_bf16_f32 v12, v16, v17
	s_waitcnt vmcnt(0)
	v_cvt_pk_bf16_f32 v13, v18, v19
	s_waitcnt lgkmcnt(0)
	s_nop 0
	v_mfma_f32_16x16x32_bf16 v[2:5], v[6:9], v[10:13], v[2:5]
	v_add_u32_e32 v6, 0x2000, v80
	s_nop 6
	ds_write2_b32 v6, v2, v3 offset1:65
	ds_write2_b32 v6, v4, v5 offset0:130 offset1:195
